# ALIGN64: the seven GEMM main-loop heads padded (s_nop before the label) to 64-byte instruction-cache-line boundaries; on top of DPP+CONV5
# baseline (speedup 1.0000x reference)
; template <class Epi, class Sched>
; __device__ __forceinline__ void gemm_phase(PG8_LAS unsigned char* lds, const Gemm g, const Sched& S, const Epi& E, int tid_in) {
;     ...
;         const bool has_next = S.next(ui + 1, nxt);
;         const char* nA = has_next ? (const char*)g.A + (size_t)nxt.pm * tstep : cA; const char* nB = has_next ? (const char*)g.Bt + (size_t)nxt.pn * tstep : cB;
;     ...
; #pragma unroll
;         for (int a = 0; a < 2; ++a)
; #pragma unroll
;             for (int b = 0; b < 2; ++b)
; #pragma unroll
;                 for (int m = 0; m < 4; ++m)
; #pragma unroll
;                     for (int n = 0; n < 2; ++n) acc[a][b][m][n] = (f32x4){0.f, 0.f, 0.f, 0.f};
.LBB0_265:
	s_ashr_i32 s15, s14, 31
	v_cmp_lt_i64_e32 vcc, s[22:23], v[242:243]
	s_lshl_b64 s[22:23], s[14:15], 21
	s_add_u32 s22, s38, s22
	s_addc_u32 s23, s39, s23
	s_and_b64 s[24:25], vcc, exec
	s_cselect_b32 s15, s23, s5
	s_cselect_b32 s52, s22, s4
	s_ashr_i32 s13, s12, 31
	s_lshl_b64 s[24:25], s[12:13], 21
	s_add_u32 s24, s40, s24
	s_addc_u32 s25, s41, s25
	s_and_b64 s[30:31], vcc, exec
	s_cselect_b32 s13, s25, s29
	s_cselect_b32 s53, s24, s28
	s_add_u32 s54, s28, 0x100
	v_mov_b32_e32 v0, 0
	s_addc_u32 s55, s29, 0
	s_mov_b32 s56, -2
	v_mov_b32_e32 v1, v0
	v_mov_b32_e32 v2, v0
	v_mov_b32_e32 v3, v0
	v_mov_b32_e32 v24, v0
	v_mov_b32_e32 v25, v0
	v_mov_b32_e32 v26, v0
	v_mov_b32_e32 v27, v0
	v_mov_b32_e32 v4, v0
	v_mov_b32_e32 v5, v0
	v_mov_b32_e32 v6, v0
	v_mov_b32_e32 v7, v0
	v_mov_b32_e32 v32, v0
	v_mov_b32_e32 v33, v0
	v_mov_b32_e32 v34, v0
	v_mov_b32_e32 v35, v0
	v_mov_b32_e32 v8, v0
	v_mov_b32_e32 v9, v0
	v_mov_b32_e32 v10, v0
	v_mov_b32_e32 v11, v0
	v_mov_b32_e32 v40, v0
	v_mov_b32_e32 v41, v0
	v_mov_b32_e32 v42, v0
	v_mov_b32_e32 v43, v0
	v_mov_b32_e32 v12, v0
	v_mov_b32_e32 v13, v0
	v_mov_b32_e32 v14, v0
	v_mov_b32_e32 v15, v0
	v_mov_b32_e32 v44, v0
	v_mov_b32_e32 v45, v0
	v_mov_b32_e32 v46, v0
	v_mov_b32_e32 v47, v0
	v_mov_b32_e32 v60, v0
	v_mov_b32_e32 v61, v0
	v_mov_b32_e32 v62, v0
	v_mov_b32_e32 v63, v0
	v_mov_b32_e32 v92, v0
	v_mov_b32_e32 v93, v0
	v_mov_b32_e32 v94, v0
	v_mov_b32_e32 v95, v0
	v_mov_b32_e32 v68, v0
	v_mov_b32_e32 v69, v0
	v_mov_b32_e32 v70, v0
	v_mov_b32_e32 v71, v0
	v_mov_b32_e32 v100, v0
	v_mov_b32_e32 v101, v0
	v_mov_b32_e32 v102, v0
	v_mov_b32_e32 v103, v0
	v_mov_b32_e32 v72, v0
	v_mov_b32_e32 v73, v0
	v_mov_b32_e32 v74, v0
	v_mov_b32_e32 v75, v0
	v_mov_b32_e32 v104, v0
	v_mov_b32_e32 v105, v0
	v_mov_b32_e32 v106, v0
	v_mov_b32_e32 v107, v0
	v_mov_b32_e32 v76, v0
	v_mov_b32_e32 v77, v0
	v_mov_b32_e32 v78, v0
	v_mov_b32_e32 v79, v0
	v_mov_b32_e32 v108, v0
	v_mov_b32_e32 v109, v0
	v_mov_b32_e32 v110, v0
	v_mov_b32_e32 v111, v0
	v_mov_b32_e32 v16, v0
	v_mov_b32_e32 v17, v0
	v_mov_b32_e32 v18, v0
	v_mov_b32_e32 v19, v0
	v_mov_b32_e32 v48, v0
	v_mov_b32_e32 v49, v0
	v_mov_b32_e32 v50, v0
	v_mov_b32_e32 v51, v0
	v_mov_b32_e32 v20, v0
	v_mov_b32_e32 v21, v0
	v_mov_b32_e32 v22, v0
	v_mov_b32_e32 v23, v0
	v_mov_b32_e32 v52, v0
	v_mov_b32_e32 v53, v0
	v_mov_b32_e32 v54, v0
	v_mov_b32_e32 v55, v0
	v_mov_b32_e32 v28, v0
	v_mov_b32_e32 v29, v0
	v_mov_b32_e32 v30, v0
	v_mov_b32_e32 v31, v0
	v_mov_b32_e32 v56, v0
	v_mov_b32_e32 v57, v0
	v_mov_b32_e32 v58, v0
	v_mov_b32_e32 v59, v0
	v_mov_b32_e32 v36, v0
	v_mov_b32_e32 v37, v0
	v_mov_b32_e32 v38, v0
	v_mov_b32_e32 v39, v0
	v_mov_b32_e32 v64, v0
	v_mov_b32_e32 v65, v0
	v_mov_b32_e32 v66, v0
	v_mov_b32_e32 v67, v0
	v_mov_b32_e32 v80, v0
	v_mov_b32_e32 v81, v0
	v_mov_b32_e32 v82, v0
	v_mov_b32_e32 v83, v0
	v_mov_b32_e32 v112, v0
	v_mov_b32_e32 v113, v0
	v_mov_b32_e32 v114, v0
	v_mov_b32_e32 v115, v0
	v_mov_b32_e32 v84, v0
	v_mov_b32_e32 v85, v0
	v_mov_b32_e32 v86, v0
	v_mov_b32_e32 v87, v0
	v_mov_b32_e32 v116, v0
	v_mov_b32_e32 v117, v0
	v_mov_b32_e32 v118, v0
	v_mov_b32_e32 v119, v0
	v_mov_b32_e32 v88, v0
	v_mov_b32_e32 v89, v0
	v_mov_b32_e32 v90, v0
	v_mov_b32_e32 v91, v0
	v_mov_b32_e32 v120, v0
	v_mov_b32_e32 v121, v0
	v_mov_b32_e32 v122, v0
	v_mov_b32_e32 v123, v0
	v_mov_b32_e32 v96, v0
	v_mov_b32_e32 v97, v0
	v_mov_b32_e32 v98, v0
	v_mov_b32_e32 v99, v0
	v_mov_b32_e32 v124, v0
	v_mov_b32_e32 v125, v0
	v_mov_b32_e32 v126, v0
	v_mov_b32_e32 v127, v0
	s_nop 0
	s_nop 0
	s_nop 0
	s_nop 0
	s_nop 0
	s_nop 0
	s_nop 0

; template <class Epi, class Sched>
; __device__ __forceinline__ void gemm_phase(PG8_LAS unsigned char* lds, const Gemm g, const Sched& S, const Epi& E, int tid_in) {
;     ...
;         const bool has_next = S.next(ui + 1, nxt);
;         const char* nA = has_next ? (const char*)g.A + (size_t)nxt.pm * tstep : cA; const char* nB = has_next ? (const char*)g.Bt + (size_t)nxt.pn * tstep : cB;
;     ...
; #pragma unroll
;         for (int a = 0; a < 2; ++a)
; #pragma unroll
;             for (int b = 0; b < 2; ++b)
; #pragma unroll
;                 for (int m = 0; m < 4; ++m)
; #pragma unroll
;                     for (int n = 0; n < 2; ++n) acc[a][b][m][n] = (f32x4){0.f, 0.f, 0.f, 0.f};
.LBB0_294:
	v_mov_b64_e32 v[0:1], 0x800
	s_ashr_i32 s9, s8, 31
	v_cmp_lt_i64_e32 vcc, s[10:11], v[0:1]
	s_lshl_b64 s[10:11], s[8:9], 19
	s_add_u32 s10, s30, s10
	s_addc_u32 s11, s31, s11
	s_and_b64 s[12:13], vcc, exec
	s_cselect_b32 s9, s11, s23
	s_cselect_b32 s45, s10, s22
	s_ashr_i32 s5, s4, 31
	s_lshl_b64 s[12:13], s[4:5], 19
	s_add_u32 s12, s36, s12
	s_addc_u32 s13, s37, s13
	s_and_b64 s[26:27], vcc, exec
	s_cselect_b32 s5, s13, s25
	s_cselect_b32 s46, s12, s24
	s_add_u32 s22, s22, 0x40080
	s_addc_u32 s23, s23, 0
	s_add_u32 s48, s24, 0x100
	v_mov_b32_e32 v0, 0
	s_addc_u32 s49, s25, 0
	s_mov_b32 s50, -2
	v_mov_b32_e32 v1, v0
	v_mov_b32_e32 v2, v0
	v_mov_b32_e32 v3, v0
	v_mov_b32_e32 v4, v0
	v_mov_b32_e32 v5, v0
	v_mov_b32_e32 v6, v0
	v_mov_b32_e32 v7, v0
	v_mov_b32_e32 v8, v0
	v_mov_b32_e32 v9, v0
	v_mov_b32_e32 v10, v0
	v_mov_b32_e32 v11, v0
	v_mov_b32_e32 v12, v0
	v_mov_b32_e32 v13, v0
	v_mov_b32_e32 v14, v0
	v_mov_b32_e32 v15, v0
	v_mov_b32_e32 v16, v0
	v_mov_b32_e32 v17, v0
	v_mov_b32_e32 v18, v0
	v_mov_b32_e32 v19, v0
	v_mov_b32_e32 v20, v0
	v_mov_b32_e32 v21, v0
	v_mov_b32_e32 v22, v0
	v_mov_b32_e32 v23, v0
	v_mov_b32_e32 v24, v0
	v_mov_b32_e32 v25, v0
	v_mov_b32_e32 v26, v0
	v_mov_b32_e32 v27, v0
	v_mov_b32_e32 v28, v0
	v_mov_b32_e32 v29, v0
	v_mov_b32_e32 v30, v0
	v_mov_b32_e32 v31, v0
	v_mov_b32_e32 v64, v0
	v_mov_b32_e32 v65, v0
	v_mov_b32_e32 v66, v0
	v_mov_b32_e32 v67, v0
	v_mov_b32_e32 v68, v0
	v_mov_b32_e32 v69, v0
	v_mov_b32_e32 v70, v0
	v_mov_b32_e32 v71, v0
	v_mov_b32_e32 v72, v0
	v_mov_b32_e32 v73, v0
	v_mov_b32_e32 v74, v0
	v_mov_b32_e32 v75, v0
	v_mov_b32_e32 v76, v0
	v_mov_b32_e32 v77, v0
	v_mov_b32_e32 v78, v0
	v_mov_b32_e32 v79, v0
	v_mov_b32_e32 v80, v0
	v_mov_b32_e32 v81, v0
	v_mov_b32_e32 v82, v0
	v_mov_b32_e32 v83, v0
	v_mov_b32_e32 v84, v0
	v_mov_b32_e32 v85, v0
	v_mov_b32_e32 v86, v0
	v_mov_b32_e32 v87, v0
	v_mov_b32_e32 v88, v0
	v_mov_b32_e32 v89, v0
	v_mov_b32_e32 v90, v0
	v_mov_b32_e32 v91, v0
	v_mov_b32_e32 v92, v0
	v_mov_b32_e32 v93, v0
	v_mov_b32_e32 v94, v0
	v_mov_b32_e32 v95, v0
	v_mov_b32_e32 v32, v0
	v_mov_b32_e32 v33, v0
	v_mov_b32_e32 v34, v0
	v_mov_b32_e32 v35, v0
	v_mov_b32_e32 v36, v0
	v_mov_b32_e32 v37, v0
	v_mov_b32_e32 v38, v0
	v_mov_b32_e32 v39, v0
	v_mov_b32_e32 v40, v0
	v_mov_b32_e32 v41, v0
	v_mov_b32_e32 v42, v0
	v_mov_b32_e32 v43, v0
	v_mov_b32_e32 v44, v0
	v_mov_b32_e32 v45, v0
	v_mov_b32_e32 v46, v0
	v_mov_b32_e32 v47, v0
	v_mov_b32_e32 v48, v0
	v_mov_b32_e32 v49, v0
	v_mov_b32_e32 v50, v0
	v_mov_b32_e32 v51, v0
	v_mov_b32_e32 v52, v0
	v_mov_b32_e32 v53, v0
	v_mov_b32_e32 v54, v0
	v_mov_b32_e32 v55, v0
	v_mov_b32_e32 v56, v0
	v_mov_b32_e32 v57, v0
	v_mov_b32_e32 v58, v0
	v_mov_b32_e32 v59, v0
	v_mov_b32_e32 v60, v0
	v_mov_b32_e32 v61, v0
	v_mov_b32_e32 v62, v0
	v_mov_b32_e32 v63, v0
	v_mov_b32_e32 v96, v0
	v_mov_b32_e32 v97, v0
	v_mov_b32_e32 v98, v0
	v_mov_b32_e32 v99, v0
	v_mov_b32_e32 v100, v0
	v_mov_b32_e32 v101, v0
	v_mov_b32_e32 v102, v0
	v_mov_b32_e32 v103, v0
	v_mov_b32_e32 v104, v0
	v_mov_b32_e32 v105, v0
	v_mov_b32_e32 v106, v0
	v_mov_b32_e32 v107, v0
	v_mov_b32_e32 v108, v0
	v_mov_b32_e32 v109, v0
	v_mov_b32_e32 v110, v0
	v_mov_b32_e32 v111, v0
	v_mov_b32_e32 v112, v0
	v_mov_b32_e32 v113, v0
	v_mov_b32_e32 v114, v0
	v_mov_b32_e32 v115, v0
	v_mov_b32_e32 v116, v0
	v_mov_b32_e32 v117, v0
	v_mov_b32_e32 v118, v0
	v_mov_b32_e32 v119, v0
	v_mov_b32_e32 v128, v0
	v_mov_b32_e32 v129, v0
	v_mov_b32_e32 v130, v0
	v_mov_b32_e32 v131, v0
	v_mov_b32_e32 v132, v0
	v_mov_b32_e32 v133, v0
	v_mov_b32_e32 v134, v0
	v_mov_b32_e32 v135, v0
	s_nop 0
	s_nop 0
	s_nop 0
	s_nop 0

; template <class Epi, class Sched>
; __device__ __forceinline__ void gemm_phase(PG8_LAS unsigned char* lds, const Gemm g, const Sched& S, const Epi& E, int tid_in) {
;     ...
;         const bool has_next = S.next(ui + 1, nxt);
;         const char* nA = has_next ? (const char*)g.A + (size_t)nxt.pm * tstep : cA; const char* nB = has_next ? (const char*)g.Bt + (size_t)nxt.pn * tstep : cB;
;     ...
; #pragma unroll
;         for (int a = 0; a < 2; ++a)
; #pragma unroll
;             for (int b = 0; b < 2; ++b)
; #pragma unroll
;                 for (int m = 0; m < 4; ++m)
; #pragma unroll
;                     for (int n = 0; n < 2; ++n) acc[a][b][m][n] = (f32x4){0.f, 0.f, 0.f, 0.f};
.LBB0_324:
	s_ashr_i32 s7, s6, 31
	v_cmp_lt_i64_e32 vcc, s[8:9], v[242:243]
	s_lshl_b64 s[8:9], s[6:7], 19
	s_add_u32 s8, s24, s8
	s_addc_u32 s9, s25, s9
	s_and_b64 s[10:11], vcc, exec
	s_cselect_b32 s7, s9, s15
	s_cselect_b32 s41, s8, s14
	s_ashr_i32 s5, s4, 31
	s_lshl_b64 s[10:11], s[4:5], 19
	s_add_u32 s10, s26, s10
	s_addc_u32 s11, s27, s11
	s_and_b64 s[18:19], vcc, exec
	s_cselect_b32 s5, s11, s17
	s_cselect_b32 s42, s10, s16
	s_add_u32 s43, s16, 0x100
	v_mov_b32_e32 v0, 0
	s_addc_u32 s44, s17, 0
	s_mov_b32 s45, -2
	v_mov_b32_e32 v1, v0
	v_mov_b32_e32 v2, v0
	v_mov_b32_e32 v3, v0
	v_mov_b32_e32 v32, v0
	v_mov_b32_e32 v33, v0
	v_mov_b32_e32 v34, v0
	v_mov_b32_e32 v35, v0
	v_mov_b32_e32 v4, v0
	v_mov_b32_e32 v5, v0
	v_mov_b32_e32 v6, v0
	v_mov_b32_e32 v7, v0
	v_mov_b32_e32 v36, v0
	v_mov_b32_e32 v37, v0
	v_mov_b32_e32 v38, v0
	v_mov_b32_e32 v39, v0
	v_mov_b32_e32 v8, v0
	v_mov_b32_e32 v9, v0
	v_mov_b32_e32 v10, v0
	v_mov_b32_e32 v11, v0
	v_mov_b32_e32 v40, v0
	v_mov_b32_e32 v41, v0
	v_mov_b32_e32 v42, v0
	v_mov_b32_e32 v43, v0
	v_mov_b32_e32 v12, v0
	v_mov_b32_e32 v13, v0
	v_mov_b32_e32 v14, v0
	v_mov_b32_e32 v15, v0
	v_mov_b32_e32 v44, v0
	v_mov_b32_e32 v45, v0
	v_mov_b32_e32 v46, v0
	v_mov_b32_e32 v47, v0
	v_mov_b32_e32 v64, v0
	v_mov_b32_e32 v65, v0
	v_mov_b32_e32 v66, v0
	v_mov_b32_e32 v67, v0
	v_mov_b32_e32 v96, v0
	v_mov_b32_e32 v97, v0
	v_mov_b32_e32 v98, v0
	v_mov_b32_e32 v99, v0
	v_mov_b32_e32 v68, v0
	v_mov_b32_e32 v69, v0
	v_mov_b32_e32 v70, v0
	v_mov_b32_e32 v71, v0
	v_mov_b32_e32 v100, v0
	v_mov_b32_e32 v101, v0
	v_mov_b32_e32 v102, v0
	v_mov_b32_e32 v103, v0
	v_mov_b32_e32 v72, v0
	v_mov_b32_e32 v73, v0
	v_mov_b32_e32 v74, v0
	v_mov_b32_e32 v75, v0
	v_mov_b32_e32 v104, v0
	v_mov_b32_e32 v105, v0
	v_mov_b32_e32 v106, v0
	v_mov_b32_e32 v107, v0
	v_mov_b32_e32 v76, v0
	v_mov_b32_e32 v77, v0
	v_mov_b32_e32 v78, v0
	v_mov_b32_e32 v79, v0
	v_mov_b32_e32 v108, v0
	v_mov_b32_e32 v109, v0
	v_mov_b32_e32 v110, v0
	v_mov_b32_e32 v111, v0
	v_mov_b32_e32 v16, v0
	v_mov_b32_e32 v17, v0
	v_mov_b32_e32 v18, v0
	v_mov_b32_e32 v19, v0
	v_mov_b32_e32 v48, v0
	v_mov_b32_e32 v49, v0
	v_mov_b32_e32 v50, v0
	v_mov_b32_e32 v51, v0
	v_mov_b32_e32 v20, v0
	v_mov_b32_e32 v21, v0
	v_mov_b32_e32 v22, v0
	v_mov_b32_e32 v23, v0
	v_mov_b32_e32 v52, v0
	v_mov_b32_e32 v53, v0
	v_mov_b32_e32 v54, v0
	v_mov_b32_e32 v55, v0
	v_mov_b32_e32 v24, v0
	v_mov_b32_e32 v25, v0
	v_mov_b32_e32 v26, v0
	v_mov_b32_e32 v27, v0
	v_mov_b32_e32 v56, v0
	v_mov_b32_e32 v57, v0
	v_mov_b32_e32 v58, v0
	v_mov_b32_e32 v59, v0
	v_mov_b32_e32 v28, v0
	v_mov_b32_e32 v29, v0
	v_mov_b32_e32 v30, v0
	v_mov_b32_e32 v31, v0
	v_mov_b32_e32 v60, v0
	v_mov_b32_e32 v61, v0
	v_mov_b32_e32 v62, v0
	v_mov_b32_e32 v63, v0
	v_mov_b32_e32 v80, v0
	v_mov_b32_e32 v81, v0
	v_mov_b32_e32 v82, v0
	v_mov_b32_e32 v83, v0
	v_mov_b32_e32 v112, v0
	v_mov_b32_e32 v113, v0
	v_mov_b32_e32 v114, v0
	v_mov_b32_e32 v115, v0
	v_mov_b32_e32 v84, v0
	v_mov_b32_e32 v85, v0
	v_mov_b32_e32 v86, v0
	v_mov_b32_e32 v87, v0
	v_mov_b32_e32 v116, v0
	v_mov_b32_e32 v117, v0
	v_mov_b32_e32 v118, v0
	v_mov_b32_e32 v119, v0
	v_mov_b32_e32 v88, v0
	v_mov_b32_e32 v89, v0
	v_mov_b32_e32 v90, v0
	v_mov_b32_e32 v91, v0
	v_mov_b32_e32 v120, v0
	v_mov_b32_e32 v121, v0
	v_mov_b32_e32 v122, v0
	v_mov_b32_e32 v123, v0
	v_mov_b32_e32 v92, v0
	v_mov_b32_e32 v93, v0
	v_mov_b32_e32 v94, v0
	v_mov_b32_e32 v95, v0
	v_mov_b32_e32 v124, v0
	v_mov_b32_e32 v125, v0
	v_mov_b32_e32 v126, v0
	v_mov_b32_e32 v127, v0
	s_nop 0
	s_nop 0
	s_nop 0
	s_nop 0
	s_nop 0
	s_nop 0

; template <class Epi, class Sched>
; __device__ __forceinline__ void gemm_phase(PG8_LAS unsigned char* lds, const Gemm g, const Sched& S, const Epi& E, int tid_in) {
;     ...
;         const bool has_next = S.next(ui + 1, nxt);
;         const char* nA = has_next ? (const char*)g.A + (size_t)nxt.pm * tstep : cA; const char* nB = has_next ? (const char*)g.Bt + (size_t)nxt.pn * tstep : cB;
;     ...
; #pragma unroll
;         for (int a = 0; a < 2; ++a)
; #pragma unroll
;             for (int b = 0; b < 2; ++b)
; #pragma unroll
;                 for (int m = 0; m < 4; ++m)
; #pragma unroll
;                     for (int n = 0; n < 2; ++n) acc[a][b][m][n] = (f32x4){0.f, 0.f, 0.f, 0.f};
.LBB0_369:
	s_ashr_i32 s11, s10, 31
	v_cmp_lt_i64_e32 vcc, s[12:13], v[242:243]
	s_lshl_b64 s[12:13], s[10:11], 19
	s_add_u32 s12, s26, s12
	s_addc_u32 s13, s27, s13
	s_and_b64 s[14:15], vcc, exec
	s_cselect_b32 s11, s13, s19
	s_cselect_b32 s41, s12, s18
	s_ashr_i32 s9, s8, 31
	s_lshl_b64 s[14:15], s[8:9], 19
	s_add_u32 s14, s28, s14
	s_addc_u32 s15, s29, s15
	s_and_b64 s[22:23], vcc, exec
	s_cselect_b32 s9, s15, s21
	s_cselect_b32 s42, s14, s20
	s_add_u32 s18, s18, 0x40080
	s_addc_u32 s19, s19, 0
	s_add_u32 s43, s20, 0x100
	v_mov_b32_e32 v0, 0
	s_addc_u32 s44, s21, 0
	s_mov_b32 s45, -2
	v_mov_b32_e32 v1, v0
	v_mov_b32_e32 v2, v0
	v_mov_b32_e32 v3, v0
	v_mov_b32_e32 v4, v0
	v_mov_b32_e32 v5, v0
	v_mov_b32_e32 v6, v0
	v_mov_b32_e32 v7, v0
	v_mov_b32_e32 v16, v0
	v_mov_b32_e32 v17, v0
	v_mov_b32_e32 v18, v0
	v_mov_b32_e32 v19, v0
	v_mov_b32_e32 v20, v0
	v_mov_b32_e32 v21, v0
	v_mov_b32_e32 v22, v0
	v_mov_b32_e32 v23, v0
	v_mov_b32_e32 v32, v0
	v_mov_b32_e32 v33, v0
	v_mov_b32_e32 v34, v0
	v_mov_b32_e32 v35, v0
	v_mov_b32_e32 v36, v0
	v_mov_b32_e32 v37, v0
	v_mov_b32_e32 v38, v0
	v_mov_b32_e32 v39, v0
	v_mov_b32_e32 v48, v0
	v_mov_b32_e32 v49, v0
	v_mov_b32_e32 v50, v0
	v_mov_b32_e32 v51, v0
	v_mov_b32_e32 v52, v0
	v_mov_b32_e32 v53, v0
	v_mov_b32_e32 v54, v0
	v_mov_b32_e32 v55, v0
	v_mov_b32_e32 v8, v0
	v_mov_b32_e32 v9, v0
	v_mov_b32_e32 v10, v0
	v_mov_b32_e32 v11, v0
	v_mov_b32_e32 v12, v0
	v_mov_b32_e32 v13, v0
	v_mov_b32_e32 v14, v0
	v_mov_b32_e32 v15, v0
	v_mov_b32_e32 v24, v0
	v_mov_b32_e32 v25, v0
	v_mov_b32_e32 v26, v0
	v_mov_b32_e32 v27, v0
	v_mov_b32_e32 v28, v0
	v_mov_b32_e32 v29, v0
	v_mov_b32_e32 v30, v0
	v_mov_b32_e32 v31, v0
	v_mov_b32_e32 v40, v0
	v_mov_b32_e32 v41, v0
	v_mov_b32_e32 v42, v0
	v_mov_b32_e32 v43, v0
	v_mov_b32_e32 v44, v0
	v_mov_b32_e32 v45, v0
	v_mov_b32_e32 v46, v0
	v_mov_b32_e32 v47, v0
	v_mov_b32_e32 v56, v0
	v_mov_b32_e32 v57, v0
	v_mov_b32_e32 v58, v0
	v_mov_b32_e32 v59, v0
	v_mov_b32_e32 v60, v0
	v_mov_b32_e32 v61, v0
	v_mov_b32_e32 v62, v0
	v_mov_b32_e32 v63, v0
	v_mov_b32_e32 v64, v0
	v_mov_b32_e32 v65, v0
	v_mov_b32_e32 v66, v0
	v_mov_b32_e32 v67, v0
	v_mov_b32_e32 v68, v0
	v_mov_b32_e32 v69, v0
	v_mov_b32_e32 v70, v0
	v_mov_b32_e32 v71, v0
	v_mov_b32_e32 v80, v0
	v_mov_b32_e32 v81, v0
	v_mov_b32_e32 v82, v0
	v_mov_b32_e32 v83, v0
	v_mov_b32_e32 v84, v0
	v_mov_b32_e32 v85, v0
	v_mov_b32_e32 v86, v0
	v_mov_b32_e32 v87, v0
	v_mov_b32_e32 v96, v0
	v_mov_b32_e32 v97, v0
	v_mov_b32_e32 v98, v0
	v_mov_b32_e32 v99, v0
	v_mov_b32_e32 v100, v0
	v_mov_b32_e32 v101, v0
	v_mov_b32_e32 v102, v0
	v_mov_b32_e32 v103, v0
	v_mov_b32_e32 v112, v0
	v_mov_b32_e32 v113, v0
	v_mov_b32_e32 v114, v0
	v_mov_b32_e32 v115, v0
	v_mov_b32_e32 v116, v0
	v_mov_b32_e32 v117, v0
	v_mov_b32_e32 v118, v0
	v_mov_b32_e32 v119, v0
	v_mov_b32_e32 v72, v0
	v_mov_b32_e32 v73, v0
	v_mov_b32_e32 v74, v0
	v_mov_b32_e32 v75, v0
	v_mov_b32_e32 v76, v0
	v_mov_b32_e32 v77, v0
	v_mov_b32_e32 v78, v0
	v_mov_b32_e32 v79, v0
	v_mov_b32_e32 v88, v0
	v_mov_b32_e32 v89, v0
	v_mov_b32_e32 v90, v0
	v_mov_b32_e32 v91, v0
	v_mov_b32_e32 v92, v0
	v_mov_b32_e32 v93, v0
	v_mov_b32_e32 v94, v0
	v_mov_b32_e32 v95, v0
	v_mov_b32_e32 v104, v0
	v_mov_b32_e32 v105, v0
	v_mov_b32_e32 v106, v0
	v_mov_b32_e32 v107, v0
	v_mov_b32_e32 v108, v0
	v_mov_b32_e32 v109, v0
	v_mov_b32_e32 v110, v0
	v_mov_b32_e32 v111, v0
	v_mov_b32_e32 v120, v0
	v_mov_b32_e32 v121, v0
	v_mov_b32_e32 v122, v0
	v_mov_b32_e32 v123, v0
	v_mov_b32_e32 v124, v0
	v_mov_b32_e32 v125, v0
	v_mov_b32_e32 v126, v0
	v_mov_b32_e32 v127, v0
	s_nop 0
	s_nop 0
	s_nop 0
	s_nop 0
	s_nop 0

; template <class Epi, class Sched>
; __device__ __forceinline__ void gemm_phase(PG8_LAS unsigned char* lds, const Gemm g, const Sched& S, const Epi& E, int tid_in) {
;     ...
;         const bool has_next = S.next(ui + 1, nxt);
;         const char* nA = has_next ? (const char*)g.A + (size_t)nxt.pm * tstep : cA; const char* nB = has_next ? (const char*)g.Bt + (size_t)nxt.pn * tstep : cB;
;     ...
; #pragma unroll
;         for (int a = 0; a < 2; ++a)
; #pragma unroll
;             for (int b = 0; b < 2; ++b)
; #pragma unroll
;                 for (int m = 0; m < 4; ++m)
; #pragma unroll
;                     for (int n = 0; n < 2; ++n) acc[a][b][m][n] = (f32x4){0.f, 0.f, 0.f, 0.f};
.LBB0_387:
	v_mov_b64_e32 v[0:1], 0xa00
	s_ashr_i32 s19, s18, 31
	v_cmp_lt_i64_e32 vcc, s[20:21], v[0:1]
	s_lshl_b64 s[20:21], s[18:19], 19
	s_add_u32 s20, s63, s20
	s_addc_u32 s21, s64, s21
	s_and_b64 s[22:23], vcc, exec
	s_cselect_b32 s1, s21, s27
	s_cselect_b32 s19, s20, s26
	s_ashr_i32 s17, s16, 31
	s_lshl_b64 s[22:23], s[16:17], 19
	s_add_u32 s22, s65, s22
	s_addc_u32 s23, s69, s23
	s_and_b64 s[30:31], vcc, exec
	s_cselect_b32 s17, s23, s29
	s_cselect_b32 s25, s22, s28
	s_add_u32 s26, s26, 0x40080
	s_addc_u32 s27, s27, 0
	s_add_u32 s33, s28, 0x100
	v_mov_b32_e32 v0, 0
	s_addc_u32 s36, s29, 0
	s_mov_b32 s37, -2
	v_mov_b32_e32 v1, v0
	v_mov_b32_e32 v2, v0
	v_mov_b32_e32 v3, v0
	v_mov_b32_e32 v4, v0
	v_mov_b32_e32 v5, v0
	v_mov_b32_e32 v6, v0
	v_mov_b32_e32 v7, v0
	v_mov_b32_e32 v16, v0
	v_mov_b32_e32 v17, v0
	v_mov_b32_e32 v18, v0
	v_mov_b32_e32 v19, v0
	v_mov_b32_e32 v20, v0
	v_mov_b32_e32 v21, v0
	v_mov_b32_e32 v22, v0
	v_mov_b32_e32 v23, v0
	v_mov_b32_e32 v32, v0
	v_mov_b32_e32 v33, v0
	v_mov_b32_e32 v34, v0
	v_mov_b32_e32 v35, v0
	v_mov_b32_e32 v36, v0
	v_mov_b32_e32 v37, v0
	v_mov_b32_e32 v38, v0
	v_mov_b32_e32 v39, v0
	v_mov_b32_e32 v48, v0
	v_mov_b32_e32 v49, v0
	v_mov_b32_e32 v50, v0
	v_mov_b32_e32 v51, v0
	v_mov_b32_e32 v52, v0
	v_mov_b32_e32 v53, v0
	v_mov_b32_e32 v54, v0
	v_mov_b32_e32 v55, v0
	v_mov_b32_e32 v8, v0
	v_mov_b32_e32 v9, v0
	v_mov_b32_e32 v10, v0
	v_mov_b32_e32 v11, v0
	v_mov_b32_e32 v12, v0
	v_mov_b32_e32 v13, v0
	v_mov_b32_e32 v14, v0
	v_mov_b32_e32 v15, v0
	v_mov_b32_e32 v24, v0
	v_mov_b32_e32 v25, v0
	v_mov_b32_e32 v26, v0
	v_mov_b32_e32 v27, v0
	v_mov_b32_e32 v28, v0
	v_mov_b32_e32 v29, v0
	v_mov_b32_e32 v30, v0
	v_mov_b32_e32 v31, v0
	v_mov_b32_e32 v40, v0
	v_mov_b32_e32 v41, v0
	v_mov_b32_e32 v42, v0
	v_mov_b32_e32 v43, v0
	v_mov_b32_e32 v44, v0
	v_mov_b32_e32 v45, v0
	v_mov_b32_e32 v46, v0
	v_mov_b32_e32 v47, v0
	v_mov_b32_e32 v56, v0
	v_mov_b32_e32 v57, v0
	v_mov_b32_e32 v58, v0
	v_mov_b32_e32 v59, v0
	v_mov_b32_e32 v60, v0
	v_mov_b32_e32 v61, v0
	v_mov_b32_e32 v62, v0
	v_mov_b32_e32 v63, v0
	v_mov_b32_e32 v64, v0
	v_mov_b32_e32 v65, v0
	v_mov_b32_e32 v66, v0
	v_mov_b32_e32 v67, v0
	v_mov_b32_e32 v68, v0
	v_mov_b32_e32 v69, v0
	v_mov_b32_e32 v70, v0
	v_mov_b32_e32 v71, v0
	v_mov_b32_e32 v80, v0
	v_mov_b32_e32 v81, v0
	v_mov_b32_e32 v82, v0
	v_mov_b32_e32 v83, v0
	v_mov_b32_e32 v84, v0
	v_mov_b32_e32 v85, v0
	v_mov_b32_e32 v86, v0
	v_mov_b32_e32 v87, v0
	v_mov_b32_e32 v96, v0
	v_mov_b32_e32 v97, v0
	v_mov_b32_e32 v98, v0
	v_mov_b32_e32 v99, v0
	v_mov_b32_e32 v100, v0
	v_mov_b32_e32 v101, v0
	v_mov_b32_e32 v102, v0
	v_mov_b32_e32 v103, v0
	v_mov_b32_e32 v112, v0
	v_mov_b32_e32 v113, v0
	v_mov_b32_e32 v114, v0
	v_mov_b32_e32 v115, v0
	v_mov_b32_e32 v116, v0
	v_mov_b32_e32 v117, v0
	v_mov_b32_e32 v118, v0
	v_mov_b32_e32 v119, v0
	v_mov_b32_e32 v72, v0
	v_mov_b32_e32 v73, v0
	v_mov_b32_e32 v74, v0
	v_mov_b32_e32 v75, v0
	v_mov_b32_e32 v76, v0
	v_mov_b32_e32 v77, v0
	v_mov_b32_e32 v78, v0
	v_mov_b32_e32 v79, v0
	v_mov_b32_e32 v88, v0
	v_mov_b32_e32 v89, v0
	v_mov_b32_e32 v90, v0
	v_mov_b32_e32 v91, v0
	v_mov_b32_e32 v92, v0
	v_mov_b32_e32 v93, v0
	v_mov_b32_e32 v94, v0
	v_mov_b32_e32 v95, v0
	v_mov_b32_e32 v104, v0
	v_mov_b32_e32 v105, v0
	v_mov_b32_e32 v106, v0
	v_mov_b32_e32 v107, v0
	v_mov_b32_e32 v108, v0
	v_mov_b32_e32 v109, v0
	v_mov_b32_e32 v110, v0
	v_mov_b32_e32 v111, v0
	s_waitcnt vmcnt(0)
	v_mov_b32_e32 v120, v0
	v_mov_b32_e32 v121, v0
	v_mov_b32_e32 v122, v0
	v_mov_b32_e32 v123, v0
	v_mov_b32_e32 v124, v0
	v_mov_b32_e32 v125, v0
	v_mov_b32_e32 v126, v0
	v_mov_b32_e32 v127, v0
	s_nop 0
	s_nop 0
	s_nop 0
	s_nop 0
	s_nop 0
	s_nop 0
	s_nop 0

; template <class Epi, class Sched>
; __device__ __forceinline__ void gemm_phase(PG8_LAS unsigned char* lds, const Gemm g, const Sched& S, const Epi& E, int tid_in) {
;     ...
;         const bool has_next = S.next(ui + 1, nxt);
;         const char* nA = has_next ? (const char*)g.A + (size_t)nxt.pm * tstep : cA; const char* nB = has_next ? (const char*)g.Bt + (size_t)nxt.pn * tstep : cB;
;     ...
; #pragma unroll
;         for (int a = 0; a < 2; ++a)
; #pragma unroll
;             for (int b = 0; b < 2; ++b)
; #pragma unroll
;                 for (int m = 0; m < 4; ++m)
; #pragma unroll
;                     for (int n = 0; n < 2; ++n) acc[a][b][m][n] = (f32x4){0.f, 0.f, 0.f, 0.f};
.LBB0_695:
	v_mov_b64_e32 v[0:1], 0xbd0
	s_ashr_i32 s11, s10, 31
	v_cmp_lt_i64_e32 vcc, s[12:13], v[0:1]
	s_lshl_b64 s[12:13], s[10:11], 19
	s_add_u32 s12, s23, s12
	s_addc_u32 s13, s24, s13
	s_and_b64 s[14:15], vcc, exec
	s_cselect_b32 s5, s13, s17
	s_cselect_b32 s7, s12, s16
	s_ashr_i32 s9, s8, 31
	s_lshl_b64 s[14:15], s[8:9], 19
	s_add_u32 s14, s25, s14
	s_addc_u32 s15, s26, s15
	s_and_b64 s[20:21], vcc, exec
	s_cselect_b32 s9, s15, s19
	s_cselect_b32 s11, s14, s18
	s_add_u32 s16, s16, 0x40080
	s_addc_u32 s17, s17, 0
	s_add_u32 s40, s18, 0x100
	v_mov_b32_e32 v0, 0
	s_addc_u32 s41, s19, 0
	s_mov_b32 s42, -2
	v_mov_b32_e32 v1, v0
	v_mov_b32_e32 v2, v0
	v_mov_b32_e32 v3, v0
	v_mov_b32_e32 v4, v0
	v_mov_b32_e32 v5, v0
	v_mov_b32_e32 v6, v0
	v_mov_b32_e32 v7, v0
	v_mov_b32_e32 v12, v0
	v_mov_b32_e32 v13, v0
	v_mov_b32_e32 v14, v0
	v_mov_b32_e32 v15, v0
	v_mov_b32_e32 v20, v0
	v_mov_b32_e32 v21, v0
	v_mov_b32_e32 v22, v0
	v_mov_b32_e32 v23, v0
	v_mov_b32_e32 v28, v0
	v_mov_b32_e32 v29, v0
	v_mov_b32_e32 v30, v0
	v_mov_b32_e32 v31, v0
	v_mov_b32_e32 v36, v0
	v_mov_b32_e32 v37, v0
	v_mov_b32_e32 v38, v0
	v_mov_b32_e32 v39, v0
	v_mov_b32_e32 v44, v0
	v_mov_b32_e32 v45, v0
	v_mov_b32_e32 v46, v0
	v_mov_b32_e32 v47, v0
	v_mov_b32_e32 v52, v0
	v_mov_b32_e32 v53, v0
	v_mov_b32_e32 v54, v0
	v_mov_b32_e32 v55, v0
	v_mov_b32_e32 v8, v0
	v_mov_b32_e32 v9, v0
	v_mov_b32_e32 v10, v0
	v_mov_b32_e32 v11, v0
	v_mov_b32_e32 v16, v0
	v_mov_b32_e32 v17, v0
	v_mov_b32_e32 v18, v0
	v_mov_b32_e32 v19, v0
	v_mov_b32_e32 v24, v0
	v_mov_b32_e32 v25, v0
	v_mov_b32_e32 v26, v0
	v_mov_b32_e32 v27, v0
	v_mov_b32_e32 v32, v0
	v_mov_b32_e32 v33, v0
	v_mov_b32_e32 v34, v0
	v_mov_b32_e32 v35, v0
	v_mov_b32_e32 v40, v0
	v_mov_b32_e32 v41, v0
	v_mov_b32_e32 v42, v0
	v_mov_b32_e32 v43, v0
	v_mov_b32_e32 v48, v0
	v_mov_b32_e32 v49, v0
	v_mov_b32_e32 v50, v0
	v_mov_b32_e32 v51, v0
	v_mov_b32_e32 v56, v0
	v_mov_b32_e32 v57, v0
	v_mov_b32_e32 v58, v0
	v_mov_b32_e32 v59, v0
	v_mov_b32_e32 v60, v0
	v_mov_b32_e32 v61, v0
	v_mov_b32_e32 v62, v0
	v_mov_b32_e32 v63, v0
	v_mov_b32_e32 v64, v0
	v_mov_b32_e32 v65, v0
	v_mov_b32_e32 v66, v0
	v_mov_b32_e32 v67, v0
	v_mov_b32_e32 v68, v0
	v_mov_b32_e32 v69, v0
	v_mov_b32_e32 v70, v0
	v_mov_b32_e32 v71, v0
	v_mov_b32_e32 v76, v0
	v_mov_b32_e32 v77, v0
	v_mov_b32_e32 v78, v0
	v_mov_b32_e32 v79, v0
	v_mov_b32_e32 v84, v0
	v_mov_b32_e32 v85, v0
	v_mov_b32_e32 v86, v0
	v_mov_b32_e32 v87, v0
	v_mov_b32_e32 v92, v0
	v_mov_b32_e32 v93, v0
	v_mov_b32_e32 v94, v0
	v_mov_b32_e32 v95, v0
	v_mov_b32_e32 v100, v0
	v_mov_b32_e32 v101, v0
	v_mov_b32_e32 v102, v0
	v_mov_b32_e32 v103, v0
	v_mov_b32_e32 v108, v0
	v_mov_b32_e32 v109, v0
	v_mov_b32_e32 v110, v0
	v_mov_b32_e32 v111, v0
	v_mov_b32_e32 v116, v0
	v_mov_b32_e32 v117, v0
	v_mov_b32_e32 v118, v0
	v_mov_b32_e32 v119, v0
	v_mov_b32_e32 v72, v0
	v_mov_b32_e32 v73, v0
	v_mov_b32_e32 v74, v0
	v_mov_b32_e32 v75, v0
	v_mov_b32_e32 v80, v0
	v_mov_b32_e32 v81, v0
	v_mov_b32_e32 v82, v0
	v_mov_b32_e32 v83, v0
	v_mov_b32_e32 v88, v0
	v_mov_b32_e32 v89, v0
	v_mov_b32_e32 v90, v0
	v_mov_b32_e32 v91, v0
	v_mov_b32_e32 v96, v0
	v_mov_b32_e32 v97, v0
	v_mov_b32_e32 v98, v0
	v_mov_b32_e32 v99, v0
	v_mov_b32_e32 v104, v0
	v_mov_b32_e32 v105, v0
	v_mov_b32_e32 v106, v0
	v_mov_b32_e32 v107, v0
	v_mov_b32_e32 v112, v0
	v_mov_b32_e32 v113, v0
	v_mov_b32_e32 v114, v0
	v_mov_b32_e32 v115, v0
	v_mov_b32_e32 v120, v0
	v_mov_b32_e32 v121, v0
	v_mov_b32_e32 v122, v0
	v_mov_b32_e32 v123, v0
	v_mov_b32_e32 v124, v0
	v_mov_b32_e32 v125, v0
	v_mov_b32_e32 v126, v0
	v_mov_b32_e32 v127, v0
	s_nop 0
	s_nop 0
	s_nop 0
	s_nop 0
	s_nop 0
	s_nop 0
	s_nop 0
	s_nop 0
	s_nop 0
	s_nop 0
	s_nop 0
	s_nop 0
	s_nop 0
	s_nop 0
	s_nop 0
